# P1 unit transition: tile index r/2, r%2 by shift and mask (gsz is always 2 here) instead of the generic reciprocal division; accumulators zeroed with 64-bit moves
# baseline (speedup 1.0000x reference)
.LBB0_102:
	s_andn2_b64 vcc, exec, s[68:69]
	s_cbranch_vccnz .LBB0_104
	s_ashr_i32 s3, s2, 31
	s_lshr_b32 s3, s3, 29
	s_add_i32 s3, s2, s3
	s_ashr_i32 s4, s3, 3
	s_and_b32 s3, s3, -8
	s_sub_i32 s2, s2, s3
	s_cmp_lt_i32 s2, 0
	s_cselect_b32 s3, s7, 0x110
	s_mul_i32 s2, s2, s3
	s_add_i32 s2, s2, s4
	s_mul_hi_i32 s3, s2, 0x78787879
	s_lshr_b32 s4, s3, 31
	s_ashr_i32 s3, s3, 5
	s_add_i32 s3, s3, s4
	s_lshl_b32 s4, s3, 1
	s_mulk_i32 s3, 0x44
	s_sub_i32 s2, s2, s3
	s_lshr_b32 s62, s2, 1
	s_and_b32 s2, s2, 1
	s_add_i32 s64, s4, s2
	s_mov_b64 s[66:67], -1
	s_mov_b32 s42, -1
.LBB0_104:
	s_ashr_i32 s65, s64, 31
	s_lshl_b64 s[2:3], s[64:65], 19
	s_add_u32 s2, s80, s2
	s_addc_u32 s3, s81, s3
	s_cmp_gt_i32 s42, 0
	s_cselect_b32 s4, 0x40000, 0
	s_add_u32 s68, s2, s4
	s_addc_u32 s69, s3, 0
	s_and_b64 s[2:3], s[66:67], exec
	s_cselect_b32 s4, s69, s77
	s_cselect_b32 s43, s68, s76
	s_ashr_i32 s63, s62, 31
	s_lshl_b64 s[2:3], s[62:63], 19
	s_add_u32 s70, s10, s2
	s_addc_u32 s71, s11, s3
	s_and_b64 s[2:3], s[66:67], exec
	s_cselect_b32 s63, s71, s1
	s_cselect_b32 s65, s70, s0
	s_cmp_lt_i32 s33, 0
	v_mov_b32_e32 v4, v2
	v_mov_b32_e32 v5, v2
	s_cselect_b64 s[86:87], -1, 0
	s_add_u32 s36, s0, 0x100
	v_mov_b32_e32 v3, v2
	v_mov_b64_e32 v[70:71], v[4:5]
	v_mov_b64_e32 v[72:73], v[4:5]
	v_mov_b64_e32 v[74:75], v[4:5]
	v_mov_b64_e32 v[76:77], v[4:5]
	v_mov_b64_e32 v[78:79], v[4:5]
	v_mov_b64_e32 v[80:81], v[4:5]
	v_mov_b64_e32 v[82:83], v[4:5]
	v_mov_b64_e32 v[84:85], v[4:5]
	v_mov_b64_e32 v[86:87], v[4:5]
	v_mov_b64_e32 v[88:89], v[4:5]
	v_mov_b64_e32 v[90:91], v[4:5]
	v_mov_b64_e32 v[92:93], v[4:5]
	v_mov_b64_e32 v[94:95], v[4:5]
	v_mov_b64_e32 v[96:97], v[4:5]
	v_mov_b64_e32 v[98:99], v[4:5]
	v_mov_b64_e32 v[100:101], v[4:5]
	v_mov_b64_e32 v[102:103], v[4:5]
	v_mov_b64_e32 v[104:105], v[4:5]
	v_mov_b64_e32 v[106:107], v[4:5]
	v_mov_b64_e32 v[108:109], v[4:5]
	v_mov_b64_e32 v[110:111], v[4:5]
	v_mov_b64_e32 v[112:113], v[4:5]
	v_mov_b64_e32 v[114:115], v[4:5]
	v_mov_b64_e32 v[116:117], v[4:5]
	v_mov_b64_e32 v[118:119], v[4:5]
	v_mov_b64_e32 v[120:121], v[4:5]
	v_mov_b64_e32 v[122:123], v[4:5]
	v_mov_b64_e32 v[124:125], v[4:5]
	v_mov_b64_e32 v[126:127], v[4:5]
	v_mov_b64_e32 v[128:129], v[4:5]
	v_mov_b64_e32 v[130:131], v[4:5]
	v_mov_b64_e32 v[132:133], v[4:5]
	v_mov_b64_e32 v[24:25], v[4:5]
	v_mov_b64_e32 v[56:57], v[4:5]
	v_mov_b64_e32 v[28:29], v[4:5]
	v_mov_b64_e32 v[60:61], v[4:5]
	v_mov_b64_e32 v[36:37], v[4:5]
	v_mov_b64_e32 v[68:69], v[4:5]
	v_mov_b64_e32 v[32:33], v[4:5]
	v_mov_b64_e32 v[64:65], v[4:5]
	v_mov_b64_e32 v[12:13], v[4:5]
	v_mov_b64_e32 v[44:45], v[4:5]
	v_mov_b64_e32 v[16:17], v[4:5]
	v_mov_b64_e32 v[48:49], v[4:5]
	v_mov_b64_e32 v[20:21], v[4:5]
	v_mov_b64_e32 v[52:53], v[4:5]
	v_mov_b64_e32 v[8:9], v[4:5]
	v_mov_b64_e32 v[40:41], v[4:5]
	s_addc_u32 s44, s1, 0
	s_mov_b32 s45, -2
	v_mov_b64_e32 v[22:23], v[2:3]
	v_mov_b64_e32 v[54:55], v[2:3]
	v_mov_b64_e32 v[26:27], v[2:3]
	v_mov_b64_e32 v[58:59], v[2:3]
	v_mov_b64_e32 v[34:35], v[2:3]
	v_mov_b64_e32 v[66:67], v[2:3]
	v_mov_b64_e32 v[30:31], v[2:3]
	v_mov_b64_e32 v[62:63], v[2:3]
	v_mov_b64_e32 v[10:11], v[2:3]
	v_mov_b64_e32 v[42:43], v[2:3]
	v_mov_b64_e32 v[14:15], v[2:3]
	v_mov_b64_e32 v[46:47], v[2:3]
	v_mov_b64_e32 v[18:19], v[2:3]
	v_mov_b64_e32 v[50:51], v[2:3]
	v_mov_b64_e32 v[6:7], v[2:3]
	v_mov_b64_e32 v[38:39], v[2:3]
	s_and_b64 vcc, exec, s[86:87]
	s_cbranch_vccnz .LBB0_107
	s_add_u32 s2, s0, 0x100
	s_addc_u32 s3, s1, 0
	s_add_u32 s84, s76, 0x100
	s_addc_u32 s85, s77, 0
	s_mov_b32 s45, 0
	s_waitcnt vmcnt(0)
	s_and_b64 vcc, exec, s[14:15]
	s_cbranch_vccnz .Lhu_loop
	v_lshl_add_u64 v[6:7], s[2:3], 0, v[208:209]
	v_lshl_add_u64 v[8:9], s[2:3], 0, v[212:213]
	s_add_u32 s88, s2, 0x40000
	s_addc_u32 s89, s3, 0
	v_lshl_add_u64 v[10:11], s[88:89], 0, v[208:209]
	v_lshl_add_u64 v[12:13], s[88:89], 0, v[212:213]
	v_lshl_add_u64 v[14:15], s[84:85], 0, v[206:207]
	v_lshl_add_u64 v[16:17], s[84:85], 0, v[210:211]
	s_add_u32 s2, s2, 0x80
	s_addc_u32 s3, s3, 0
	s_add_u32 s84, s84, 0x80
	s_addc_u32 s85, s85, 0
	s_add_i32 m0, s61, 0xc000
	s_nop 0
	global_load_lds_dwordx4 v[6:7], off
	s_add_i32 m0, s61, 0xe000
	s_nop 0
	global_load_lds_dwordx4 v[8:9], off
	s_add_i32 m0, s61, 0x20000
	s_nop 0
	global_load_lds_dwordx4 v[10:11], off
	s_add_i32 m0, s61, 0x22000
	s_nop 0
	global_load_lds_dwordx4 v[12:13], off
	s_mov_b32 m0, s95
	s_nop 0
	global_load_lds_dwordx4 v[14:15], off
	s_mov_b32 m0, s96
	s_nop 0
	global_load_lds_dwordx4 v[16:17], off
